# v8 + ClusterFinish first poll issued before the first weight DMA pieces and retired with vmcnt(4)
# baseline (speedup 1.0000x reference)
.LBB0_99:
	s_and_b64 vcc, exec, s[6:7]
	s_cbranch_vccz .LBB0_132
	v_ashrrev_i32_e32 v3, 31, v2
	v_lshrrev_b32_e32 v3, 26, v3
	v_add_u32_e32 v3, v2, v3
	v_ashrrev_i32_e32 v4, 6, v3
	v_bfe_i32 v3, v2, 27, 1
	v_lshlrev_b32_e32 v5, 4, v2
	v_lshrrev_b32_e32 v3, 22, v3
	v_add_u32_e32 v3, v5, v3
	v_and_b32_e32 v3, 0xfffffc00, v3
	v_sub_u32_e32 v3, v5, v3
	v_lshrrev_b32_e32 v6, 4, v3
	v_bitop3_b32 v6, v6, v3, 32 bitop3:0x6c
	v_ashrrev_i32_e32 v7, 31, v6
	v_lshrrev_b32_e32 v7, 26, v7
	v_add_u32_e32 v7, v6, v7
	v_ashrrev_i32_e32 v8, 6, v7
	v_and_b32_e32 v7, 0xc0, v7
	v_sub_u32_e32 v6, v6, v7
	v_mov_b32_e32 v7, 1
	v_lshlrev_b32_e32 v3, 3, v4
	v_lshlrev_b32_e32 v4, 5, v4
	v_ashrrev_i16_sdwa v6, v7, sext(v6) dst_sel:DWORD dst_unused:UNUSED_PAD src0_sel:DWORD src1_sel:BYTE_0
	v_and_b32_e32 v3, -16, v3
	v_and_b32_e32 v4, 32, v4
	v_bfe_i32 v6, v6, 0, 16
	v_add_u32_e32 v5, 0x2000, v5
	v_add_u32_e32 v3, v8, v3
	v_add_lshl_u32 v4, v4, v6, 1
	v_ashrrev_i32_e32 v6, 31, v5
	v_lshlrev_b32_e32 v9, 1, v3
	v_lshrrev_b32_e32 v10, 2, v3
	v_and_b32_e32 v8, 3, v8
	s_mov_b32 s7, 0x1fffe0
	v_lshrrev_b32_e32 v6, 22, v6
	v_and_b32_e32 v9, 24, v9
	v_and_b32_e32 v10, 4, v10
	v_and_or_b32 v8, v3, s7, v8
	v_add_u32_e32 v6, v5, v6
	v_or3_b32 v8, v8, v10, v9
	v_ashrrev_i32_e32 v6, 10, v6
	v_lshl_add_u32 v154, v8, 11, v4
	v_mul_i32_i24_e32 v8, 0x400, v6
	v_sub_u32_e32 v5, v5, v8
	v_lshrrev_b32_e32 v8, 4, v5
	v_bitop3_b32 v8, v8, v5, 32 bitop3:0x6c
	v_ashrrev_i32_e32 v9, 31, v8
	v_lshrrev_b32_e32 v9, 26, v9
	v_lshlrev_b32_e32 v5, 3, v6
	v_add_u32_e32 v9, v8, v9
	s_add_u32 s8, s2, 0x200000
	v_and_b32_e32 v5, -16, v5
	v_ashrrev_i32_e32 v10, 6, v9
	s_addc_u32 s6, s3, 0
	v_add_u32_e32 v5, v10, v5
	v_and_b32_e32 v10, 3, v10
	s_ashr_i32 s20, s18, 31
	v_and_or_b32 v10, v5, s7, v10
	s_lshr_b32 s7, s20, 29
	s_add_i32 s7, s18, s7
	s_ashr_i32 s34, s41, 6
	s_ashr_i32 s12, s7, 3
	s_and_b32 s7, s7, -8
	s_and_b32 s9, s6, 0xffff
	s_lshl_b32 s6, s34, 10
	s_sub_i32 s7, s18, s7
	s_cmp_lt_i32 s7, 0
	s_movk_i32 s13, 0x61
	s_cselect_b32 s13, s13, 0x60
	s_mul_i32 s7, s7, s13
	s_add_i32 s7, s7, s12
	s_mul_hi_i32 s12, s7, 0x2aaaaaab
	s_lshr_b32 s13, s12, 31
	s_ashr_i32 s26, s12, 4
	s_add_i32 s26, s26, s13
	s_mul_i32 s12, s26, 0x60
	s_sub_i32 s27, s7, s12
	s_bfe_i32 s7, s27, 0x80000
	s_bfe_u32 s7, s7, 0x3000c
	v_and_b32_e32 v9, 0xc0, v9
	s_add_i32 s7, s27, s7
	v_sub_u32_e32 v8, v8, v9
	s_bfe_i32 s7, s7, 0x80000
	v_lshlrev_b32_e32 v6, 5, v6
	v_ashrrev_i16_sdwa v7, v7, sext(v8) dst_sel:DWORD dst_unused:UNUSED_PAD src0_sel:DWORD src1_sel:BYTE_0
	v_lshlrev_b32_e32 v8, 1, v5
	v_lshrrev_b32_e32 v9, 2, v5
	s_sext_i32_i16 s28, s7
	v_and_b32_e32 v6, 32, v6
	v_bfe_i32 v7, v7, 0, 16
	v_and_b32_e32 v8, 24, v8
	v_and_b32_e32 v9, 4, v9
	s_ashr_i32 s46, s28, 3
	s_add_i32 s21, s6, 0
	v_or3_b32 v8, v10, v9, v8
	v_add_lshl_u32 v6, v6, v7, 1
	s_mov_b32 s11, 0x20000
	s_mov_b32 s10, -1
	s_lshl_b32 s53, s46, 19
	s_add_i32 s22, s21, 0x10000
	v_mov_b32_e32 v254, 0
	global_load_dword v255, v254, s[4:5] sc1
	s_mov_b32 m0, s22
	s_nop 0
	buffer_load_dwordx4 v154, s[8:11], s53 offen lds
	v_lshl_add_u32 v155, v8, 11, v6
	s_add_i32 s23, s21, 0x12000
	s_mov_b32 m0, s23
	s_nop 0
	buffer_load_dwordx4 v155, s[8:11], s53 offen lds
	s_add_i32 s24, s21, 0x14000
	s_or_b32 s6, s53, 0x40000
	s_mov_b32 m0, s24
	s_nop 0
	buffer_load_dwordx4 v154, s[8:11], s6 offen lds
	s_add_i32 s25, s21, 0x16000
	s_mov_b32 m0, s25
	s_nop 0
	buffer_load_dwordx4 v155, s[8:11], s6 offen lds
	v_cmp_eq_u32_e32 vcc, 0, v0
	s_and_saveexec_b64 s[6:7], vcc
	s_cbranch_execz .LBB0_113
	v_mov_b32_e32 v7, 0
	s_waitcnt vmcnt(4)
	v_cmp_lt_u32_e32 vcc, 3, v255
	s_cbranch_vccnz .LBB0_113
	s_mov_b32 s29, 1
	s_branch .LBB0_104

.LBB0_199:
	v_bfe_i32 v4, v210, 27, 1
	v_lshlrev_b32_e32 v2, 4, v210
	v_lshrrev_b32_e32 v4, 22, v4
	v_add_u32_e32 v4, v2, v4
	v_and_b32_e32 v4, 0xfffffc00, v4
	v_sub_u32_e32 v4, v2, v4
	v_lshrrev_b32_e32 v5, 4, v4
	v_bitop3_b32 v4, v5, v4, 32 bitop3:0x6c
	v_ashrrev_i32_e32 v3, 31, v210
	v_ashrrev_i32_e32 v6, 31, v4
	v_lshrrev_b32_e32 v3, 26, v3
	v_lshrrev_b32_e32 v6, 26, v6
	v_add_u32_e32 v3, v210, v3
	v_add_u32_e32 v6, v4, v6
	v_ashrrev_i32_e32 v3, 6, v3
	v_lshrrev_b32_e32 v7, 6, v6
	v_and_b32_e32 v6, 0xc0, v6
	v_lshlrev_b32_e32 v5, 3, v3
	v_lshlrev_b32_e32 v3, 5, v3
	v_sub_u32_e32 v4, v4, v6
	v_mov_b32_e32 v6, 1
	v_and_b32_e32 v5, 0x1ffff0, v5
	v_and_b32_e32 v3, 32, v3
	v_ashrrev_i16_sdwa v4, v6, sext(v4) dst_sel:DWORD dst_unused:UNUSED_PAD src0_sel:DWORD src1_sel:BYTE_0
	v_add_u32_sdwa v3, v3, sext(v4) dst_sel:DWORD dst_unused:UNUSED_PAD src0_sel:DWORD src1_sel:WORD_0
	v_add_lshl_u32 v4, v7, v5, 11
	v_add_u32_e32 v2, 0x2000, v2
	v_lshl_add_u32 v130, v3, 1, v4
	v_ashrrev_i32_e32 v3, 31, v2
	s_add_u32 s8, s16, 0x800000
	v_lshrrev_b32_e32 v3, 22, v3
	s_addc_u32 s5, s17, 0
	v_add_u32_e32 v3, v2, v3
	s_add_i32 s4, s6, s4
	v_ashrrev_i32_e32 v3, 10, v3
	s_ashr_i32 s6, s4, 31
	v_mul_i32_i24_e32 v4, 0x400, v3
	s_lshr_b32 s6, s6, 27
	v_sub_u32_e32 v2, v2, v4
	s_add_i32 s28, s4, s6
	v_lshrrev_b32_e32 v4, 4, v2
	s_and_b32 s6, s28, 0xffe0
	v_bitop3_b32 v2, v4, v2, 32 bitop3:0x6c
	s_sub_i32 s24, s4, s6
	v_ashrrev_i32_e32 v5, 31, v2
	s_bfe_i32 s4, s24, 0x80000
	v_lshrrev_b32_e32 v5, 26, v5
	s_bfe_u32 s4, s4, 0x3000c
	v_add_u32_e32 v5, v2, v5
	s_add_i32 s4, s24, s4
	s_ashr_i32 s19, s27, 6
	v_lshrrev_b32_e32 v7, 6, v5
	v_and_b32_e32 v5, 0xc0, v5
	s_bfe_i32 s4, s4, 0x80000
	v_lshlrev_b32_e32 v4, 3, v3
	v_lshlrev_b32_e32 v3, 5, v3
	v_sub_u32_e32 v2, v2, v5
	s_and_b32 s9, s5, 0xffff
	s_lshl_b32 s5, s19, 10
	s_sext_i32_i16 s29, s4
	v_and_b32_e32 v4, 0x1ffff0, v4
	v_and_b32_e32 v3, 32, v3
	v_ashrrev_i16_sdwa v2, v6, sext(v2) dst_sel:DWORD dst_unused:UNUSED_PAD src0_sel:DWORD src1_sel:BYTE_0
	s_ashr_i32 s18, s29, 3
	s_add_i32 s31, s5, 0
	v_add_u32_sdwa v2, v3, sext(v2) dst_sel:DWORD dst_unused:UNUSED_PAD src0_sel:DWORD src1_sel:WORD_0
	v_add_lshl_u32 v3, v7, v4, 11
	s_mov_b32 s11, 0x20000
	s_mov_b32 s10, -1
	s_lshl_b32 s34, s18, 19
	s_add_i32 s33, s31, 0x10000
	v_mov_b32_e32 v254, 0
	global_load_dword v255, v254, s[2:3] sc1
	s_mov_b32 m0, s33
	s_nop 0
	buffer_load_dwordx4 v130, s[8:11], s34 offen lds
	v_lshl_add_u32 v131, v2, 1, v3
	s_add_i32 s35, s31, 0x12000
	s_mov_b32 m0, s35
	s_nop 0
	buffer_load_dwordx4 v131, s[8:11], s34 offen lds
	s_add_i32 s36, s31, 0x14000
	s_or_b32 s4, s34, 0x40000
	s_mov_b32 m0, s36
	s_nop 0
	buffer_load_dwordx4 v130, s[8:11], s4 offen lds
	s_add_i32 s37, s31, 0x16000
	s_mov_b32 m0, s37
	s_nop 0
	buffer_load_dwordx4 v131, s[8:11], s4 offen lds
	s_and_saveexec_b64 s[4:5], s[56:57]
	s_cbranch_execz .LBB0_212
	v_mov_b32_e32 v2, 0
	s_waitcnt vmcnt(4)
	v_cmp_lt_u32_e32 vcc, 11, v255
	s_cbranch_vccnz .LBB0_212
	s_mov_b32 s38, 1
	s_branch .LBB0_203

.LBB0_326:
	s_and_b64 vcc, exec, s[4:5]
	s_cbranch_vccz .LBB0_341
	v_ashrrev_i32_e32 v3, 31, v2
	v_lshrrev_b32_e32 v3, 26, v3
	v_add_u32_e32 v3, v2, v3
	v_ashrrev_i32_e32 v4, 6, v3
	v_bfe_i32 v3, v2, 27, 1
	v_lshlrev_b32_e32 v5, 4, v2
	v_lshrrev_b32_e32 v3, 22, v3
	v_add_u32_e32 v3, v5, v3
	v_and_b32_e32 v3, 0xfffffc00, v3
	v_sub_u32_e32 v3, v5, v3
	v_lshrrev_b32_e32 v6, 4, v3
	v_bitop3_b32 v6, v6, v3, 32 bitop3:0x6c
	v_ashrrev_i32_e32 v7, 31, v6
	v_lshrrev_b32_e32 v7, 26, v7
	v_add_u32_e32 v7, v6, v7
	v_ashrrev_i32_e32 v8, 6, v7
	v_and_b32_e32 v7, 0xc0, v7
	v_sub_u32_e32 v6, v6, v7
	v_mov_b32_e32 v7, 1
	v_lshlrev_b32_e32 v3, 3, v4
	v_lshlrev_b32_e32 v4, 5, v4
	v_ashrrev_i16_sdwa v6, v7, sext(v6) dst_sel:DWORD dst_unused:UNUSED_PAD src0_sel:DWORD src1_sel:BYTE_0
	v_and_b32_e32 v3, -16, v3
	v_and_b32_e32 v4, 32, v4
	v_bfe_i32 v6, v6, 0, 16
	v_add_u32_e32 v5, 0x2000, v5
	v_add_u32_e32 v3, v8, v3
	v_add_lshl_u32 v4, v4, v6, 1
	v_ashrrev_i32_e32 v6, 31, v5
	v_lshlrev_b32_e32 v9, 1, v3
	v_lshrrev_b32_e32 v10, 2, v3
	v_and_b32_e32 v8, 3, v8
	s_mov_b32 s5, 0x3fffe0
	v_lshrrev_b32_e32 v6, 22, v6
	v_and_b32_e32 v9, 24, v9
	v_and_b32_e32 v10, 4, v10
	v_and_or_b32 v8, v3, s5, v8
	v_add_u32_e32 v6, v5, v6
	v_or3_b32 v8, v8, v10, v9
	v_ashrrev_i32_e32 v6, 10, v6
	v_lshl_add_u32 v145, v8, 10, v4
	v_mul_i32_i24_e32 v8, 0x400, v6
	v_sub_u32_e32 v5, v5, v8
	v_lshrrev_b32_e32 v8, 4, v5
	v_bitop3_b32 v8, v8, v5, 32 bitop3:0x6c
	v_ashrrev_i32_e32 v9, 31, v8
	v_lshrrev_b32_e32 v9, 26, v9
	v_lshlrev_b32_e32 v5, 3, v6
	v_add_u32_e32 v9, v8, v9
	s_add_u32 s8, s16, 0xa00000
	v_and_b32_e32 v5, -16, v5
	v_ashrrev_i32_e32 v10, 6, v9
	s_addc_u32 s4, s17, 0
	v_add_u32_e32 v5, v10, v5
	v_and_b32_e32 v10, 3, v10
	s_ashr_i32 s31, s28, 31
	v_and_or_b32 v10, v5, s5, v10
	s_lshr_b32 s5, s31, 29
	s_add_i32 s5, s28, s5
	s_ashr_i32 s25, s24, 6
	s_ashr_i32 s6, s5, 3
	s_and_b32 s5, s5, -8
	s_and_b32 s9, s4, 0xffff
	s_lshl_b32 s4, s25, 10
	s_sub_i32 s5, s28, s5
	s_cmp_lt_i32 s5, 0
	s_movk_i32 s7, 0xb1
	s_cselect_b32 s7, s7, 0xb0
	s_mul_i32 s5, s5, s7
	s_add_i32 s5, s5, s6
	s_mul_hi_i32 s6, s5, 0x2e8ba2e9
	s_lshr_b32 s7, s6, 31
	s_ashr_i32 s20, s6, 5
	s_add_i32 s20, s20, s7
	s_mul_i32 s6, s20, 0xb0
	s_sub_i32 s21, s5, s6
	v_and_b32_e32 v9, 0xc0, v9
	s_bfe_u32 s5, s21, 0x3001c
	v_sub_u32_e32 v8, v8, v9
	s_add_i32 s5, s21, s5
	v_lshlrev_b32_e32 v6, 5, v6
	v_ashrrev_i16_sdwa v7, v7, sext(v8) dst_sel:DWORD dst_unused:UNUSED_PAD src0_sel:DWORD src1_sel:BYTE_0
	v_lshlrev_b32_e32 v8, 1, v5
	v_lshrrev_b32_e32 v9, 2, v5
	s_sext_i32_i16 s22, s5
	v_and_b32_e32 v6, 32, v6
	v_bfe_i32 v7, v7, 0, 16
	v_and_b32_e32 v8, 24, v8
	v_and_b32_e32 v9, 4, v9
	s_ashr_i32 s60, s22, 3
	s_add_i32 s33, s4, 0
	v_or3_b32 v8, v10, v9, v8
	v_add_lshl_u32 v6, v6, v7, 1
	s_mov_b32 s11, 0x20000
	s_mov_b32 s10, -1
	s_lshl_b32 s64, s60, 18
	s_add_i32 s34, s33, 0x10000
	v_mov_b32_e32 v254, 0
	global_load_dword v255, v254, s[2:3] sc1
	s_mov_b32 m0, s34
	s_nop 0
	buffer_load_dwordx4 v145, s[8:11], s64 offen lds
	v_lshl_add_u32 v146, v8, 10, v6
	s_add_i32 s35, s33, 0x12000
	s_mov_b32 m0, s35
	s_nop 0
	buffer_load_dwordx4 v146, s[8:11], s64 offen lds
	s_add_i32 s36, s33, 0x14000
	s_or_b32 s4, s64, 0x20000
	s_mov_b32 m0, s36
	s_nop 0
	buffer_load_dwordx4 v145, s[8:11], s4 offen lds
	s_add_i32 s37, s33, 0x16000
	s_mov_b32 m0, s37
	s_nop 0
	buffer_load_dwordx4 v146, s[8:11], s4 offen lds
	s_and_saveexec_b64 s[4:5], s[56:57]
	s_cbranch_execz .LBB0_345
	v_mov_b32_e32 v7, 0
	s_waitcnt vmcnt(4)
	v_cmp_lt_u32_e32 vcc, 19, v255
	s_cbranch_vccnz .LBB0_345
	s_mov_b32 s23, 1
	s_branch .LBB0_331

.LBB0_438:
	s_and_b64 vcc, exec, s[2:3]
	s_cbranch_vccz .LBB0_525
	v_bfe_i32 v4, v146, 27, 1
	v_lshlrev_b32_e32 v2, 4, v146
	v_lshrrev_b32_e32 v4, 22, v4
	v_add_u32_e32 v4, v2, v4
	v_and_b32_e32 v4, 0xfffffc00, v4
	v_sub_u32_e32 v4, v2, v4
	v_ashrrev_i32_e32 v3, 31, v146
	v_lshrrev_b32_e32 v5, 4, v4
	v_lshrrev_b32_e32 v3, 26, v3
	v_bitop3_b32 v4, v5, v4, 32 bitop3:0x6c
	v_add_u32_e32 v3, v146, v3
	v_ashrrev_i32_e32 v6, 31, v4
	v_ashrrev_i32_e32 v3, 6, v3
	v_lshrrev_b32_e32 v6, 26, v6
	v_lshlrev_b32_e32 v5, 3, v3
	v_add_u32_e32 v6, v4, v6
	v_and_b32_e32 v5, 0xfffff0, v5
	v_lshrrev_b32_e32 v7, 6, v6
	v_and_b32_e32 v6, 0xc0, v6
	v_add_u32_e32 v5, v7, v5
	v_sub_u32_e32 v4, v4, v6
	v_mov_b32_e32 v6, 1
	s_movk_i32 s3, 0xb00
	v_lshlrev_b32_e32 v3, 5, v3
	v_ashrrev_i16_sdwa v4, v6, sext(v4) dst_sel:DWORD dst_unused:UNUSED_PAD src0_sel:DWORD src1_sel:BYTE_0
	v_mul_lo_u32 v5, v5, s3
	v_bfe_i32 v4, v4, 0, 16
	v_and_or_b32 v3, v3, 32, v5
	v_add_u32_e32 v2, 0x2000, v2
	v_add_lshl_u32 v130, v3, v4, 1
	v_ashrrev_i32_e32 v3, 31, v2
	v_lshrrev_b32_e32 v3, 22, v3
	v_add_u32_e32 v3, v2, v3
	v_ashrrev_i32_e32 v3, 10, v3
	v_mul_i32_i24_e32 v4, 0x400, v3
	v_sub_u32_e32 v2, v2, v4
	v_lshrrev_b32_e32 v4, 4, v2
	v_bitop3_b32 v2, v4, v2, 32 bitop3:0x6c
	v_ashrrev_i32_e32 v5, 31, v2
	v_lshrrev_b32_e32 v5, 26, v5
	s_add_u32 s8, s16, 0x2000000
	v_lshlrev_b32_e32 v4, 3, v3
	v_add_u32_e32 v5, v2, v5
	s_addc_u32 s2, s17, 0
	s_ashr_i32 s19, s27, 6
	v_and_b32_e32 v4, 0xfffff0, v4
	v_lshrrev_b32_e32 v7, 6, v5
	v_and_b32_e32 v5, 0xc0, v5
	v_add_u32_e32 v4, v7, v4
	v_sub_u32_e32 v2, v2, v5
	s_and_b32 s9, s2, 0xffff
	s_lshl_b32 s2, s19, 10
	v_lshlrev_b32_e32 v3, 5, v3
	v_ashrrev_i16_sdwa v2, v6, sext(v2) dst_sel:DWORD dst_unused:UNUSED_PAD src0_sel:DWORD src1_sel:BYTE_0
	v_mul_lo_u32 v4, v4, s3
	s_add_i32 s28, s2, 0
	v_bfe_i32 v2, v2, 0, 16
	v_and_or_b32 v3, v3, 32, v4
	s_mov_b32 s11, 0x20000
	s_mov_b32 s10, -1
	s_mul_i32 s33, s18, 0x160000
	s_add_i32 s29, s28, 0x10000
	v_mov_b32_e32 v254, 0
	global_load_dword v255, v254, s[0:1] sc1
	s_mov_b32 m0, s29
	s_nop 0
	buffer_load_dwordx4 v130, s[8:11], s33 offen lds
	v_add_lshl_u32 v131, v3, v2, 1
	s_add_i32 s34, s28, 0x12000
	s_mov_b32 m0, s34
	s_nop 0
	buffer_load_dwordx4 v131, s[8:11], s33 offen lds
	s_add_i32 s35, s28, 0x14000
	s_add_i32 s2, s33, 0xb0000
	s_mov_b32 m0, s35
	s_nop 0
	buffer_load_dwordx4 v130, s[8:11], s2 offen lds
	s_add_i32 s36, s28, 0x16000
	s_mov_b32 m0, s36
	s_nop 0
	buffer_load_dwordx4 v131, s[8:11], s2 offen lds
	s_and_saveexec_b64 s[2:3], s[56:57]
	s_cbranch_execz .LBB0_452
	v_mov_b32_e32 v2, 0
	s_waitcnt vmcnt(4)
	v_cmp_lt_u32_e32 vcc, 23, v255
	s_cbranch_vccnz .LBB0_452
	s_mov_b32 s14, 1
	s_branch .LBB0_443

.LBB0_590:
	s_and_b64 vcc, exec, s[4:5]
	s_cbranch_vccz .LBB0_605
	v_ashrrev_i32_e32 v3, 31, v2
	v_lshrrev_b32_e32 v3, 26, v3
	v_add_u32_e32 v3, v2, v3
	v_ashrrev_i32_e32 v4, 6, v3
	v_bfe_i32 v3, v2, 27, 1
	v_lshlrev_b32_e32 v5, 4, v2
	v_lshrrev_b32_e32 v3, 22, v3
	v_add_u32_e32 v3, v5, v3
	v_and_b32_e32 v3, 0xfffffc00, v3
	v_sub_u32_e32 v3, v5, v3
	v_lshrrev_b32_e32 v6, 4, v3
	v_bitop3_b32 v6, v6, v3, 32 bitop3:0x6c
	v_ashrrev_i32_e32 v7, 31, v6
	v_lshrrev_b32_e32 v7, 26, v7
	v_add_u32_e32 v7, v6, v7
	v_ashrrev_i32_e32 v8, 6, v7
	v_and_b32_e32 v7, 0xc0, v7
	v_sub_u32_e32 v6, v6, v7
	v_mov_b32_e32 v7, 1
	v_lshlrev_b32_e32 v3, 3, v4
	v_lshlrev_b32_e32 v4, 5, v4
	v_ashrrev_i16_sdwa v6, v7, sext(v6) dst_sel:DWORD dst_unused:UNUSED_PAD src0_sel:DWORD src1_sel:BYTE_0
	v_and_b32_e32 v3, -16, v3
	v_and_b32_e32 v4, 32, v4
	v_bfe_i32 v6, v6, 0, 16
	v_add_u32_e32 v5, 0x2000, v5
	v_add_u32_e32 v3, v8, v3
	v_add_lshl_u32 v4, v4, v6, 1
	v_ashrrev_i32_e32 v6, 31, v5
	v_lshlrev_b32_e32 v9, 1, v3
	v_lshrrev_b32_e32 v10, 2, v3
	v_and_b32_e32 v8, 3, v8
	s_mov_b32 s5, 0x3fffe0
	v_lshrrev_b32_e32 v6, 22, v6
	v_and_b32_e32 v9, 24, v9
	v_and_b32_e32 v10, 4, v10
	v_and_or_b32 v8, v3, s5, v8
	v_add_u32_e32 v6, v5, v6
	v_or3_b32 v8, v8, v10, v9
	v_ashrrev_i32_e32 v6, 10, v6
	v_lshl_add_u32 v204, v8, 10, v4
	v_mul_i32_i24_e32 v8, 0x400, v6
	v_sub_u32_e32 v5, v5, v8
	v_lshrrev_b32_e32 v8, 4, v5
	v_bitop3_b32 v8, v8, v5, 32 bitop3:0x6c
	v_ashrrev_i32_e32 v9, 31, v8
	v_lshrrev_b32_e32 v9, 26, v9
	v_lshlrev_b32_e32 v5, 3, v6
	v_add_u32_e32 v9, v8, v9
	s_add_u32 s12, s20, 0x2b00000
	v_and_b32_e32 v5, -16, v5
	v_ashrrev_i32_e32 v10, 6, v9
	v_and_b32_e32 v9, 0xc0, v9
	s_addc_u32 s4, s21, 0
	s_ashr_i32 s34, s36, 6
	v_add_u32_e32 v5, v10, v5
	v_sub_u32_e32 v8, v8, v9
	v_lshlrev_b32_e32 v6, 5, v6
	v_ashrrev_i16_sdwa v7, v7, sext(v8) dst_sel:DWORD dst_unused:UNUSED_PAD src0_sel:DWORD src1_sel:BYTE_0
	v_lshlrev_b32_e32 v8, 1, v5
	v_lshrrev_b32_e32 v9, 2, v5
	v_and_b32_e32 v10, 3, v10
	s_and_b32 s13, s4, 0xffff
	s_lshl_b32 s4, s34, 10
	v_and_b32_e32 v6, 32, v6
	v_bfe_i32 v7, v7, 0, 16
	v_and_b32_e32 v8, 24, v8
	v_and_b32_e32 v9, 4, v9
	v_and_or_b32 v10, v5, s5, v10
	s_add_i32 s47, s4, 0
	v_or3_b32 v8, v10, v9, v8
	v_add_lshl_u32 v6, v6, v7, 1
	s_mov_b32 s15, 0x20000
	s_mov_b32 s14, -1
	s_lshl_b32 s41, s33, 18
	s_add_i32 s48, s47, 0x10000
	v_mov_b32_e32 v254, 0
	global_load_dword v255, v254, s[2:3] sc1
	s_mov_b32 m0, s48
	s_nop 0
	buffer_load_dwordx4 v204, s[12:15], s41 offen lds
	v_lshl_add_u32 v205, v8, 10, v6
	s_add_i32 s49, s47, 0x12000
	s_mov_b32 m0, s49
	s_nop 0
	buffer_load_dwordx4 v205, s[12:15], s41 offen lds
	s_add_i32 s50, s47, 0x14000
	s_or_b32 s4, s41, 0x20000
	s_mov_b32 m0, s50
	s_nop 0
	buffer_load_dwordx4 v204, s[12:15], s4 offen lds
	s_add_i32 s51, s47, 0x16000
	s_mov_b32 m0, s51
	s_nop 0
	buffer_load_dwordx4 v205, s[12:15], s4 offen lds
	s_and_saveexec_b64 s[4:5], s[56:57]
	s_cbranch_execz .LBB0_609
	v_mov_b32_e32 v7, 0
	s_waitcnt vmcnt(4)
	v_cmp_lt_u32_e32 vcc, 31, v255
	s_cbranch_vccnz .LBB0_609
	s_mov_b32 s16, 1
	s_branch .LBB0_595

.LBB0_919:
	v_bfe_i32 v4, v241, 27, 1
	v_lshlrev_b32_e32 v2, 4, v241
	v_lshrrev_b32_e32 v4, 22, v4
	v_add_u32_e32 v4, v2, v4
	v_and_b32_e32 v4, 0xfffffc00, v4
	v_sub_u32_e32 v4, v2, v4
	v_lshrrev_b32_e32 v5, 4, v4
	v_bitop3_b32 v4, v5, v4, 32 bitop3:0x6c
	v_ashrrev_i32_e32 v3, 31, v241
	v_ashrrev_i32_e32 v6, 31, v4
	v_lshrrev_b32_e32 v3, 26, v3
	v_lshrrev_b32_e32 v6, 26, v6
	v_add_u32_e32 v3, v241, v3
	v_add_u32_e32 v6, v4, v6
	v_ashrrev_i32_e32 v3, 6, v3
	v_lshrrev_b32_e32 v7, 6, v6
	v_and_b32_e32 v6, 0xc0, v6
	v_lshlrev_b32_e32 v5, 3, v3
	v_lshlrev_b32_e32 v3, 5, v3
	v_sub_u32_e32 v4, v4, v6
	v_mov_b32_e32 v8, 1
	v_and_b32_e32 v5, 0x3ffff0, v5
	v_and_b32_e32 v3, 32, v3
	v_ashrrev_i16_sdwa v4, v8, sext(v4) dst_sel:DWORD dst_unused:UNUSED_PAD src0_sel:DWORD src1_sel:BYTE_0
	v_add_u32_sdwa v3, v3, sext(v4) dst_sel:DWORD dst_unused:UNUSED_PAD src0_sel:DWORD src1_sel:WORD_0
	v_add_lshl_u32 v4, v7, v5, 10
	v_add_u32_e32 v2, 0x2000, v2
	v_lshl_add_u32 v6, v3, 1, v4
	v_ashrrev_i32_e32 v3, 31, v2
	s_add_u32 s8, s16, 0x2e00000
	v_lshrrev_b32_e32 v3, 22, v3
	s_addc_u32 s3, s17, 0
	v_add_u32_e32 v3, v2, v3
	s_add_i32 s2, s4, s2
	v_ashrrev_i32_e32 v3, 10, v3
	s_ashr_i32 s4, s2, 31
	v_mul_i32_i24_e32 v4, 0x400, v3
	s_lshr_b32 s4, s4, 27
	v_sub_u32_e32 v2, v2, v4
	s_add_i32 s15, s2, s4
	v_lshrrev_b32_e32 v4, 4, v2
	s_and_b32 s4, s15, 0xffe0
	v_bitop3_b32 v2, v4, v2, 32 bitop3:0x6c
	s_sub_i32 s14, s2, s4
	v_ashrrev_i32_e32 v5, 31, v2
	s_bfe_i32 s2, s14, 0x80000
	v_lshrrev_b32_e32 v5, 26, v5
	s_bfe_u32 s2, s2, 0x3000c
	v_add_u32_e32 v5, v2, v5
	s_add_i32 s2, s14, s2
	s_ashr_i32 s19, s26, 6
	v_lshrrev_b32_e32 v7, 6, v5
	v_and_b32_e32 v5, 0xc0, v5
	s_bfe_i32 s2, s2, 0x80000
	v_lshlrev_b32_e32 v4, 3, v3
	v_lshlrev_b32_e32 v3, 5, v3
	v_sub_u32_e32 v2, v2, v5
	s_and_b32 s9, s3, 0xffff
	s_lshl_b32 s3, s19, 10
	s_sext_i32_i16 s30, s2
	v_and_b32_e32 v4, 0x3ffff0, v4
	v_and_b32_e32 v3, 32, v3
	v_ashrrev_i16_sdwa v2, v8, sext(v2) dst_sel:DWORD dst_unused:UNUSED_PAD src0_sel:DWORD src1_sel:BYTE_0
	s_ashr_i32 s18, s30, 3
	s_add_i32 s28, s3, 0
	v_add_u32_sdwa v2, v3, sext(v2) dst_sel:DWORD dst_unused:UNUSED_PAD src0_sel:DWORD src1_sel:WORD_0
	v_add_lshl_u32 v3, v7, v4, 10
	s_mov_b32 s11, 0x20000
	s_mov_b32 s10, -1
	s_lshl_b32 s33, s18, 18
	s_add_i32 s29, s28, 0x10000
	v_mov_b32_e32 v254, 0
	global_load_dword v255, v254, s[0:1] sc1
	s_mov_b32 m0, s29
	s_nop 0
	buffer_load_dwordx4 v6, s[8:11], s33 offen lds
	v_lshl_add_u32 v7, v2, 1, v3
	s_add_i32 s34, s28, 0x12000
	s_mov_b32 m0, s34
	s_nop 0
	buffer_load_dwordx4 v7, s[8:11], s33 offen lds
	s_add_i32 s35, s28, 0x14000
	s_or_b32 s2, s33, 0x20000
	s_mov_b32 m0, s35
	s_nop 0
	buffer_load_dwordx4 v6, s[8:11], s2 offen lds
	s_add_i32 s36, s28, 0x16000
	s_mov_b32 m0, s36
	s_nop 0
	buffer_load_dwordx4 v7, s[8:11], s2 offen lds
	s_and_saveexec_b64 s[2:3], s[56:57]
	s_cbranch_execz .LBB0_932
	v_mov_b32_e32 v2, 0
	s_waitcnt vmcnt(4)
	v_cmp_lt_u32_e32 vcc, 39, v255
	s_cbranch_vccnz .LBB0_932
	s_mov_b32 s31, 1
	s_branch .LBB0_923

.LBB0_1050:
	s_and_b64 vcc, exec, s[6:7]
	s_cbranch_vccz .LBB0_1079
	v_ashrrev_i32_e32 v3, 31, v2
	v_lshrrev_b32_e32 v3, 26, v3
	v_add_u32_e32 v3, v2, v3
	v_ashrrev_i32_e32 v4, 6, v3
	v_bfe_i32 v3, v2, 27, 1
	v_lshlrev_b32_e32 v5, 4, v2
	v_lshrrev_b32_e32 v3, 22, v3
	v_add_u32_e32 v3, v5, v3
	v_and_b32_e32 v3, 0xfffffc00, v3
	v_sub_u32_e32 v3, v5, v3
	v_lshrrev_b32_e32 v6, 4, v3
	v_bitop3_b32 v6, v6, v3, 32 bitop3:0x6c
	v_ashrrev_i32_e32 v7, 31, v6
	v_lshrrev_b32_e32 v7, 26, v7
	v_add_u32_e32 v7, v6, v7
	v_ashrrev_i32_e32 v8, 6, v7
	v_and_b32_e32 v7, 0xc0, v7
	v_sub_u32_e32 v6, v6, v7
	v_mov_b32_e32 v7, 1
	v_lshlrev_b32_e32 v3, 3, v4
	v_lshlrev_b32_e32 v4, 5, v4
	v_ashrrev_i16_sdwa v6, v7, sext(v6) dst_sel:DWORD dst_unused:UNUSED_PAD src0_sel:DWORD src1_sel:BYTE_0
	v_and_b32_e32 v3, -16, v3
	v_and_b32_e32 v4, 32, v4
	v_bfe_i32 v6, v6, 0, 16
	v_add_u32_e32 v5, 0x2000, v5
	v_add_u32_e32 v3, v8, v3
	v_add_lshl_u32 v4, v4, v6, 1
	v_ashrrev_i32_e32 v6, 31, v5
	v_lshlrev_b32_e32 v9, 1, v3
	v_lshrrev_b32_e32 v10, 2, v3
	v_and_b32_e32 v8, 3, v8
	s_mov_b32 s7, 0x3fffe0
	v_lshrrev_b32_e32 v6, 22, v6
	v_and_b32_e32 v9, 24, v9
	v_and_b32_e32 v10, 4, v10
	v_and_or_b32 v8, v3, s7, v8
	v_add_u32_e32 v6, v5, v6
	v_or3_b32 v8, v8, v10, v9
	v_ashrrev_i32_e32 v6, 10, v6
	v_lshl_add_u32 v144, v8, 10, v4
	v_mul_i32_i24_e32 v8, 0x400, v6
	v_sub_u32_e32 v5, v5, v8
	v_lshrrev_b32_e32 v8, 4, v5
	v_bitop3_b32 v8, v8, v5, 32 bitop3:0x6c
	v_ashrrev_i32_e32 v9, 31, v8
	v_lshrrev_b32_e32 v9, 26, v9
	v_lshlrev_b32_e32 v5, 3, v6
	v_add_u32_e32 v9, v8, v9
	s_add_u32 s8, s0, 0x1500000
	v_and_b32_e32 v5, -16, v5
	v_ashrrev_i32_e32 v10, 6, v9
	s_addc_u32 s6, s1, 0
	v_add_u32_e32 v5, v10, v5
	v_and_b32_e32 v10, 3, v10
	s_ashr_i32 s25, s24, 31
	v_and_or_b32 v10, v5, s7, v10
	s_lshr_b32 s7, s25, 29
	s_add_i32 s7, s24, s7
	s_ashr_i32 s21, s20, 6
	s_ashr_i32 s12, s7, 3
	s_and_b32 s7, s7, -8
	s_and_b32 s9, s6, 0xffff
	s_lshl_b32 s6, s21, 10
	s_sub_i32 s7, s24, s7
	s_cmp_lt_i32 s7, 0
	s_movk_i32 s13, 0xb1
	s_cselect_b32 s13, s13, 0xb0
	s_mul_i32 s7, s7, s13
	s_add_i32 s7, s7, s12
	s_mul_hi_i32 s12, s7, 0x2e8ba2e9
	s_lshr_b32 s13, s12, 31
	s_ashr_i32 s18, s12, 5
	s_add_i32 s18, s18, s13
	s_mul_i32 s12, s18, 0xb0
	s_sub_i32 s19, s7, s12
	v_and_b32_e32 v9, 0xc0, v9
	s_bfe_u32 s7, s19, 0x3001c
	v_sub_u32_e32 v8, v8, v9
	s_add_i32 s7, s19, s7
	v_lshlrev_b32_e32 v6, 5, v6
	v_ashrrev_i16_sdwa v7, v7, sext(v8) dst_sel:DWORD dst_unused:UNUSED_PAD src0_sel:DWORD src1_sel:BYTE_0
	v_lshlrev_b32_e32 v8, 1, v5
	v_lshrrev_b32_e32 v9, 2, v5
	s_sext_i32_i16 s22, s7
	v_and_b32_e32 v6, 32, v6
	v_bfe_i32 v7, v7, 0, 16
	v_and_b32_e32 v8, 24, v8
	v_and_b32_e32 v9, 4, v9
	s_ashr_i32 s52, s22, 3
	s_add_i32 s26, s6, 0
	v_or3_b32 v8, v10, v9, v8
	v_add_lshl_u32 v6, v6, v7, 1
	s_mov_b32 s11, 0x20000
	s_mov_b32 s10, -1
	s_lshl_b32 s58, s52, 18
	s_add_i32 s27, s26, 0x10000
	v_mov_b32_e32 v254, 0
	global_load_dword v255, v254, s[4:5] sc1
	s_mov_b32 m0, s27
	s_nop 0
	buffer_load_dwordx4 v144, s[8:11], s58 offen lds
	v_lshl_add_u32 v145, v8, 10, v6
	s_add_i32 s28, s26, 0x12000
	s_mov_b32 m0, s28
	s_nop 0
	buffer_load_dwordx4 v145, s[8:11], s58 offen lds
	s_add_i32 s29, s26, 0x14000
	s_or_b32 s6, s58, 0x20000
	s_mov_b32 m0, s29
	s_nop 0
	buffer_load_dwordx4 v144, s[8:11], s6 offen lds
	s_add_i32 s30, s26, 0x16000
	s_mov_b32 m0, s30
	s_nop 0
	buffer_load_dwordx4 v145, s[8:11], s6 offen lds
	s_and_saveexec_b64 s[6:7], s[56:57]
	s_cbranch_execz .LBB0_1064
	v_mov_b32_e32 v7, 0
	s_waitcnt vmcnt(4)
	v_cmp_lt_u32_e32 vcc, 47, v255
	s_cbranch_vccnz .LBB0_1064
	s_mov_b32 s31, 1
	s_branch .LBB0_1055

.LBB0_1101:
	s_and_b64 vcc, exec, s[2:3]
	s_cbranch_vccz .LBB0_1116
	v_bfe_i32 v4, v0, 27, 1
	v_lshlrev_b32_e32 v2, 4, v0
	v_lshrrev_b32_e32 v4, 22, v4
	v_add_u32_e32 v4, v2, v4
	v_and_b32_e32 v4, 0xfffffc00, v4
	v_sub_u32_e32 v4, v2, v4
	v_ashrrev_i32_e32 v3, 31, v0
	v_lshrrev_b32_e32 v5, 4, v4
	v_lshrrev_b32_e32 v3, 26, v3
	v_bitop3_b32 v4, v5, v4, 32 bitop3:0x6c
	v_add_u32_e32 v3, v0, v3
	v_ashrrev_i32_e32 v6, 31, v4
	v_ashrrev_i32_e32 v3, 6, v3
	v_lshrrev_b32_e32 v6, 26, v6
	v_lshlrev_b32_e32 v5, 3, v3
	v_add_u32_e32 v6, v4, v6
	v_and_b32_e32 v5, 0xfffff0, v5
	v_lshrrev_b32_e32 v7, 6, v6
	v_and_b32_e32 v6, 0xc0, v6
	v_add_u32_e32 v5, v7, v5
	v_sub_u32_e32 v4, v4, v6
	v_mov_b32_e32 v6, 1
	s_movk_i32 s3, 0xb00
	v_lshlrev_b32_e32 v3, 5, v3
	v_ashrrev_i16_sdwa v4, v6, sext(v4) dst_sel:DWORD dst_unused:UNUSED_PAD src0_sel:DWORD src1_sel:BYTE_0
	v_mul_lo_u32 v5, v5, s3
	v_bfe_i32 v4, v4, 0, 16
	v_and_or_b32 v3, v3, 32, v5
	v_add_u32_e32 v2, 0x2000, v2
	v_add_lshl_u32 v134, v3, v4, 1
	v_ashrrev_i32_e32 v3, 31, v2
	v_lshrrev_b32_e32 v3, 22, v3
	v_add_u32_e32 v3, v2, v3
	v_ashrrev_i32_e32 v3, 10, v3
	v_mul_i32_i24_e32 v4, 0x400, v3
	v_sub_u32_e32 v2, v2, v4
	v_lshrrev_b32_e32 v4, 4, v2
	v_bitop3_b32 v2, v4, v2, 32 bitop3:0x6c
	v_ashrrev_i32_e32 v5, 31, v2
	v_lshrrev_b32_e32 v5, 26, v5
	s_add_u32 s12, s10, 0x2580000
	v_lshlrev_b32_e32 v4, 3, v3
	v_add_u32_e32 v5, v2, v5
	s_addc_u32 s2, s11, 0
	s_ashr_i32 s21, s27, 6
	v_and_b32_e32 v4, 0xfffff0, v4
	v_lshrrev_b32_e32 v7, 6, v5
	v_and_b32_e32 v5, 0xc0, v5
	v_add_u32_e32 v4, v7, v4
	v_sub_u32_e32 v2, v2, v5
	s_and_b32 s13, s2, 0xffff
	s_lshl_b32 s2, s21, 10
	v_lshlrev_b32_e32 v3, 5, v3
	v_ashrrev_i16_sdwa v2, v6, sext(v2) dst_sel:DWORD dst_unused:UNUSED_PAD src0_sel:DWORD src1_sel:BYTE_0
	v_mul_lo_u32 v4, v4, s3
	s_add_i32 s28, s2, 0
	v_bfe_i32 v2, v2, 0, 16
	v_and_or_b32 v3, v3, 32, v4
	s_mov_b32 s15, 0x20000
	s_mov_b32 s14, -1
	s_mul_i32 s30, s20, 0x160000
	s_add_i32 s29, s28, 0x10000
	v_mov_b32_e32 v254, 0
	global_load_dword v255, v254, s[0:1] sc1
	s_mov_b32 m0, s29
	s_nop 0
	buffer_load_dwordx4 v134, s[12:15], s30 offen lds
	v_add_lshl_u32 v135, v3, v2, 1
	s_add_i32 s33, s28, 0x12000
	s_mov_b32 m0, s33
	s_nop 0
	buffer_load_dwordx4 v135, s[12:15], s30 offen lds
	s_add_i32 s34, s28, 0x14000
	s_add_i32 s2, s30, 0xb0000
	s_mov_b32 m0, s34
	s_nop 0
	buffer_load_dwordx4 v134, s[12:15], s2 offen lds
	s_add_i32 s35, s28, 0x16000
	s_mov_b32 m0, s35
	s_nop 0
	buffer_load_dwordx4 v135, s[12:15], s2 offen lds
	s_and_saveexec_b64 s[2:3], s[56:57]
	s_cbranch_execz .LBB0_1120
	v_mov_b32_e32 v2, 0
	s_waitcnt vmcnt(4)
	v_cmp_lt_u32_e32 vcc, 51, v255
	s_cbranch_vccnz .LBB0_1120
	s_mov_b32 s24, 1
	s_branch .LBB0_1106
